# phase 7: first dot of each accumulator uses v_dot2_f32_bf16 with the zero register as addend instead of v_mov + v_dot2c
# speedup vs baseline: 1.0245x; 1.0014x over previous
.LBB0_1043:
	s_cmp_lt_u32 s28, 8
	s_cselect_b64 s[2:3], -1, 0
	s_and_b32 s10, s27, 56
	v_or_b32_e32 v0, s10, v85
	v_cndmask_b32_e64 v4, v102, v101, s[2:3]
	v_lshlrev_b32_e32 v5, 2, v0
	ds_bpermute_b32 v98, v5, v4
	s_waitcnt lgkmcnt(0)
	v_lshlrev_b64 v[0:1], 9, v[98:99]
	ds_bpermute_b32 v98, v5, v4 offset:8
	v_lshl_add_u64 v[2:3], v[18:19], 0, v[0:1]
	v_lshl_add_u64 v[0:1], v[20:21], 0, v[0:1]
	global_load_dwordx4 v[108:111], v[2:3], off
	global_load_dwordx4 v[12:15], v[0:1], off
	s_waitcnt lgkmcnt(0)
	v_lshlrev_b64 v[0:1], 9, v[98:99]
	ds_bpermute_b32 v98, v5, v4 offset:16
	v_lshl_add_u64 v[2:3], v[18:19], 0, v[0:1]
	v_lshl_add_u64 v[0:1], v[20:21], 0, v[0:1]
	global_load_dwordx4 v[112:115], v[2:3], off
	global_load_dwordx4 v[8:11], v[0:1], off
	s_waitcnt lgkmcnt(0)
	v_lshlrev_b64 v[0:1], 9, v[98:99]
	ds_bpermute_b32 v98, v5, v4 offset:24
	v_lshl_add_u64 v[2:3], v[18:19], 0, v[0:1]
	v_lshl_add_u64 v[0:1], v[20:21], 0, v[0:1]
	global_load_dwordx4 v[116:119], v[2:3], off
	global_load_dwordx4 v[4:7], v[0:1], off
	s_waitcnt lgkmcnt(0)
	v_lshlrev_b64 v[0:1], 9, v[98:99]
	v_lshl_add_u64 v[124:125], v[18:19], 0, v[0:1]
	v_lshl_add_u64 v[126:127], v[20:21], 0, v[0:1]
	global_load_dwordx4 v[120:123], v[124:125], off
	global_load_dwordx4 v[0:3], v[126:127], off
	v_cndmask_b32_e64 v125, v107, v105, s[2:3]
	s_waitcnt vmcnt(8)
	v_cndmask_b32_e64 v126, v104, v103, s[2:3]
	s_waitcnt vmcnt(7)
	v_cvt_scalef32_pk_bf16_fp4 v127, v108, 1.0
	v_cvt_scalef32_pk_bf16_fp4 v128, v108, 1.0 op_sel:[1,0,0]
	v_cvt_scalef32_pk_bf16_fp4 v129, v108, 1.0 op_sel:[0,1,0]
	v_dot2_f32_bf16 v98, v127, v66, v99
	v_cvt_scalef32_pk_bf16_fp4 v108, v108, 1.0 op_sel:[1,1,0]
	v_cvt_scalef32_pk_bf16_fp4 v130, v109, 1.0
	v_dot2_f32_bf16 v124, v128, v67, v99
	v_dot2c_f32_bf16_e32 v98, v129, v68
	v_cvt_scalef32_pk_bf16_fp4 v131, v109, 1.0 op_sel:[1,0,0]
	v_cvt_scalef32_pk_bf16_fp4 v132, v109, 1.0 op_sel:[0,1,0]
	v_dot2c_f32_bf16_e32 v124, v108, v69
	v_dot2c_f32_bf16_e32 v98, v130, v70
	v_cvt_scalef32_pk_bf16_fp4 v109, v109, 1.0 op_sel:[1,1,0]
	v_cvt_scalef32_pk_bf16_fp4 v133, v110, 1.0
	v_dot2c_f32_bf16_e32 v124, v131, v71
	v_dot2c_f32_bf16_e32 v98, v132, v72
	v_cvt_scalef32_pk_bf16_fp4 v134, v110, 1.0 op_sel:[1,0,0]
	v_cvt_scalef32_pk_bf16_fp4 v135, v110, 1.0 op_sel:[0,1,0]
	v_dot2c_f32_bf16_e32 v124, v109, v73
	v_dot2c_f32_bf16_e32 v98, v133, v74
	v_cvt_scalef32_pk_bf16_fp4 v110, v110, 1.0 op_sel:[1,1,0]
	v_dot2c_f32_bf16_e32 v124, v134, v75
	v_dot2c_f32_bf16_e32 v98, v135, v76
	v_cvt_scalef32_pk_bf16_fp4 v108, v111, 1.0
	v_dot2c_f32_bf16_e32 v124, v110, v77
	v_dot2c_f32_bf16_e32 v98, v108, v78
	v_cvt_scalef32_pk_bf16_fp4 v108, v111, 1.0 op_sel:[1,0,0]
	v_dot2c_f32_bf16_e32 v124, v108, v79
	v_cvt_scalef32_pk_bf16_fp4 v108, v111, 1.0 op_sel:[0,1,0]
	v_dot2c_f32_bf16_e32 v98, v108, v80
	v_cvt_scalef32_pk_bf16_fp4 v108, v111, 1.0 op_sel:[1,1,0]
	v_dot2c_f32_bf16_e32 v124, v108, v81
	s_nop 2
	v_add_f32_e32 v98, v98, v124
	s_waitcnt vmcnt(5)
	v_cvt_scalef32_pk_bf16_fp4 v108, v112, 1.0
	v_dot2_f32_bf16 v109, v108, v66, v99
	v_cvt_scalef32_pk_bf16_fp4 v108, v112, 1.0 op_sel:[1,0,0]
	v_dot2_f32_bf16 v110, v108, v67, v99
	v_cvt_scalef32_pk_bf16_fp4 v108, v112, 1.0 op_sel:[0,1,0]
	v_dot2c_f32_bf16_e32 v109, v108, v68
	v_cvt_scalef32_pk_bf16_fp4 v108, v112, 1.0 op_sel:[1,1,0]
	v_dot2c_f32_bf16_e32 v110, v108, v69
	v_cvt_scalef32_pk_bf16_fp4 v108, v113, 1.0
	v_dot2c_f32_bf16_e32 v109, v108, v70
	v_cvt_scalef32_pk_bf16_fp4 v108, v113, 1.0 op_sel:[1,0,0]
	v_dot2c_f32_bf16_e32 v110, v108, v71
	v_cvt_scalef32_pk_bf16_fp4 v108, v113, 1.0 op_sel:[0,1,0]
	v_dot2c_f32_bf16_e32 v109, v108, v72
	v_cvt_scalef32_pk_bf16_fp4 v108, v113, 1.0 op_sel:[1,1,0]
	v_dot2c_f32_bf16_e32 v110, v108, v73
	v_cvt_scalef32_pk_bf16_fp4 v108, v114, 1.0
	v_dot2c_f32_bf16_e32 v109, v108, v74
	v_cvt_scalef32_pk_bf16_fp4 v108, v114, 1.0 op_sel:[1,0,0]
	v_dot2c_f32_bf16_e32 v110, v108, v75
	v_cvt_scalef32_pk_bf16_fp4 v108, v114, 1.0 op_sel:[0,1,0]
	v_dot2c_f32_bf16_e32 v109, v108, v76
	v_cvt_scalef32_pk_bf16_fp4 v108, v114, 1.0 op_sel:[1,1,0]
	v_dot2c_f32_bf16_e32 v110, v108, v77
	v_cvt_scalef32_pk_bf16_fp4 v108, v115, 1.0
	v_dot2c_f32_bf16_e32 v109, v108, v78
	v_cvt_scalef32_pk_bf16_fp4 v108, v115, 1.0 op_sel:[1,0,0]
	v_dot2c_f32_bf16_e32 v110, v108, v79
	v_cvt_scalef32_pk_bf16_fp4 v108, v115, 1.0 op_sel:[0,1,0]
	v_dot2c_f32_bf16_e32 v109, v108, v80
	v_cvt_scalef32_pk_bf16_fp4 v108, v115, 1.0 op_sel:[1,1,0]
	v_dot2c_f32_bf16_e32 v110, v108, v81
	s_nop 2
	v_add_f32_e32 v108, v109, v110
	s_waitcnt vmcnt(3)
	v_cvt_scalef32_pk_bf16_fp4 v109, v116, 1.0
	v_dot2_f32_bf16 v110, v109, v66, v99
	v_cvt_scalef32_pk_bf16_fp4 v109, v116, 1.0 op_sel:[1,0,0]
	v_dot2_f32_bf16 v111, v109, v67, v99
	v_cvt_scalef32_pk_bf16_fp4 v109, v116, 1.0 op_sel:[0,1,0]
	v_dot2c_f32_bf16_e32 v110, v109, v68
	v_cvt_scalef32_pk_bf16_fp4 v109, v116, 1.0 op_sel:[1,1,0]
	v_dot2c_f32_bf16_e32 v111, v109, v69
	v_cvt_scalef32_pk_bf16_fp4 v109, v117, 1.0
	v_dot2c_f32_bf16_e32 v110, v109, v70
	v_cvt_scalef32_pk_bf16_fp4 v109, v117, 1.0 op_sel:[1,0,0]
	v_dot2c_f32_bf16_e32 v111, v109, v71
	v_cvt_scalef32_pk_bf16_fp4 v109, v117, 1.0 op_sel:[0,1,0]
	v_dot2c_f32_bf16_e32 v110, v109, v72
	v_cvt_scalef32_pk_bf16_fp4 v109, v117, 1.0 op_sel:[1,1,0]
	v_dot2c_f32_bf16_e32 v111, v109, v73
	v_cvt_scalef32_pk_bf16_fp4 v109, v118, 1.0
	v_dot2c_f32_bf16_e32 v110, v109, v74
	v_cvt_scalef32_pk_bf16_fp4 v109, v118, 1.0 op_sel:[1,0,0]
	v_dot2c_f32_bf16_e32 v111, v109, v75
	v_cvt_scalef32_pk_bf16_fp4 v109, v118, 1.0 op_sel:[0,1,0]
	v_dot2c_f32_bf16_e32 v110, v109, v76
	v_cvt_scalef32_pk_bf16_fp4 v109, v118, 1.0 op_sel:[1,1,0]
	v_dot2c_f32_bf16_e32 v111, v109, v77
	v_cvt_scalef32_pk_bf16_fp4 v109, v119, 1.0
	v_dot2c_f32_bf16_e32 v110, v109, v78
	v_cvt_scalef32_pk_bf16_fp4 v109, v119, 1.0 op_sel:[1,0,0]
	v_dot2c_f32_bf16_e32 v111, v109, v79
	v_cvt_scalef32_pk_bf16_fp4 v109, v119, 1.0 op_sel:[0,1,0]
	v_dot2c_f32_bf16_e32 v110, v109, v80
	v_cvt_scalef32_pk_bf16_fp4 v109, v119, 1.0 op_sel:[1,1,0]
	v_dot2c_f32_bf16_e32 v111, v109, v81
	s_nop 2
	v_add_f32_e32 v109, v110, v111
	s_waitcnt vmcnt(1)
	v_cvt_scalef32_pk_bf16_fp4 v110, v120, 1.0
	v_dot2_f32_bf16 v111, v110, v66, v99
	v_cvt_scalef32_pk_bf16_fp4 v110, v120, 1.0 op_sel:[1,0,0]
	v_dot2_f32_bf16 v112, v110, v67, v99
	v_cvt_scalef32_pk_bf16_fp4 v110, v120, 1.0 op_sel:[0,1,0]
	v_dot2c_f32_bf16_e32 v111, v110, v68
	v_cvt_scalef32_pk_bf16_fp4 v110, v120, 1.0 op_sel:[1,1,0]
	v_dot2c_f32_bf16_e32 v112, v110, v69
	v_cvt_scalef32_pk_bf16_fp4 v110, v121, 1.0
	v_dot2c_f32_bf16_e32 v111, v110, v70
	v_cvt_scalef32_pk_bf16_fp4 v110, v121, 1.0 op_sel:[1,0,0]
	v_dot2c_f32_bf16_e32 v112, v110, v71
	v_cvt_scalef32_pk_bf16_fp4 v110, v121, 1.0 op_sel:[0,1,0]
	v_dot2c_f32_bf16_e32 v111, v110, v72
	v_cvt_scalef32_pk_bf16_fp4 v110, v121, 1.0 op_sel:[1,1,0]
	v_dot2c_f32_bf16_e32 v112, v110, v73
	v_cvt_scalef32_pk_bf16_fp4 v110, v122, 1.0
	v_dot2c_f32_bf16_e32 v111, v110, v74
	v_cvt_scalef32_pk_bf16_fp4 v110, v122, 1.0 op_sel:[1,0,0]
	v_dot2c_f32_bf16_e32 v112, v110, v75
	v_cvt_scalef32_pk_bf16_fp4 v110, v122, 1.0 op_sel:[0,1,0]
	v_dot2c_f32_bf16_e32 v111, v110, v76
	v_cvt_scalef32_pk_bf16_fp4 v110, v122, 1.0 op_sel:[1,1,0]
	v_dot2c_f32_bf16_e32 v112, v110, v77
	v_cvt_scalef32_pk_bf16_fp4 v110, v123, 1.0
	v_dot2c_f32_bf16_e32 v111, v110, v78
	v_cvt_scalef32_pk_bf16_fp4 v110, v123, 1.0 op_sel:[1,0,0]
	v_dot2c_f32_bf16_e32 v112, v110, v79
	v_cvt_scalef32_pk_bf16_fp4 v110, v123, 1.0 op_sel:[0,1,0]
	v_dot2c_f32_bf16_e32 v111, v110, v80
	v_cvt_scalef32_pk_bf16_fp4 v110, v123, 1.0 op_sel:[1,1,0]
	v_dot2c_f32_bf16_e32 v112, v110, v81
	s_nop 2
	v_add_f32_e32 v110, v111, v112
	v_cndmask_b32_e32 v111, v98, v109, vcc
	v_cndmask_b32_e32 v112, v108, v110, vcc
	ds_bpermute_b32 v111, v82, v111
	ds_bpermute_b32 v112, v82, v112
	v_cndmask_b32_e32 v98, v109, v98, vcc
	v_cndmask_b32_e32 v108, v110, v108, vcc
	v_or_b32_e32 v110, s10, v86
	s_waitcnt lgkmcnt(1)
	v_add_f32_e32 v98, v98, v111
	s_waitcnt lgkmcnt(0)
	v_add_f32_e32 v108, v108, v112
	v_cndmask_b32_e64 v109, v98, v108, s[0:1]
	ds_bpermute_b32 v109, v83, v109
	v_lshlrev_b32_e32 v110, 2, v110
	v_cndmask_b32_e64 v98, v108, v98, s[0:1]
	ds_bpermute_b32 v108, v110, v126
	s_waitcnt lgkmcnt(1)
	v_add_f32_e32 v98, v98, v109
	s_nop 1
	v_add_f32_dpp v98, v98, v98 row_half_mirror row_mask:0xf bank_mask:0xf bound_ctrl:1
	s_nop 1
	v_add_f32_dpp v109, v98, v98 quad_perm:[2,3,0,1] row_mask:0xf bank_mask:0xf bound_ctrl:1
	ds_bpermute_b32 v98, v110, v125
	s_nop 0
	v_add_f32_dpp v109, v109, v109 quad_perm:[1,0,3,2] row_mask:0xf bank_mask:0xf bound_ctrl:1
	s_waitcnt lgkmcnt(1)
	v_mul_f32_e32 v108, v109, v108
	v_mul_f32_e32 v109, 0x3f3504f3, v108
	v_cmp_nlt_f32_e64 s[2:3], |v109|, 1.0
	s_and_saveexec_b64 s[10:11], s[2:3]
	s_xor_b64 s[10:11], exec, s[10:11]
	s_cbranch_execz .LBB0_1045
	v_fma_f32 v110, |v109|, s12, v97
	v_fma_f32 v110, |v109|, v110, s13
	v_fma_f32 v110, |v109|, v110, s14
	v_fma_f32 v110, |v109|, v110, s15
	v_fma_f32 v110, |v109|, v110, s16
	v_fma_f32 v110, |v109|, v110, s17
	v_fma_f32 v110, |v109|, v110, |v109|
	v_mul_f32_e32 v111, 0xbfb8aa3b, v110
	v_fma_f32 v112, v110, s18, -v111
	v_rndne_f32_e32 v113, v111
	v_fmac_f32_e32 v112, 0xb2a5705f, v110
	v_sub_f32_e32 v111, v111, v113
	v_add_f32_e32 v111, v111, v112
	v_cvt_i32_f32_e32 v112, v113
	v_exp_f32_e32 v111, v111
	v_cmp_nlt_f32_e64 s[2:3], s19, v110
	v_ldexp_f32 v111, v111, v112
	s_nop 0
	v_cndmask_b32_e64 v111, 0, v111, s[2:3]
	v_cmp_ngt_f32_e64 s[2:3], s20, v110
	s_nop 1
	v_cndmask_b32_e64 v110, v100, v111, s[2:3]
	v_sub_f32_e32 v110, 1.0, v110
